# v31 + attention A/D row-max trees: 119 canonicalizing v_max x,x removed by operand forwarding (exact for MFMA outputs)
# speedup vs baseline: 1.0060x; 1.0060x over previous
.LBB0_231:
	s_or_b64 exec, exec, s[8:9]
	v_lshl_add_u64 v[2:3], s[2:3], 1, v[120:121]
	global_load_dwordx4 v[2:5], v[2:3], off
	ds_read_b128 v[10:13], v137
	ds_read_b128 v[64:67], v137 offset:32
	s_waitcnt lgkmcnt(1)
	v_mfma_f32_32x32x16_bf16 v[48:63], v[10:13], v[80:83], 0
	ds_read_b128 v[10:13], v137 offset:64
	s_waitcnt lgkmcnt(1)
	v_mfma_f32_32x32x16_bf16 v[48:63], v[64:67], v[84:87], v[48:63]
	s_waitcnt lgkmcnt(0)
	v_mfma_f32_32x32x16_bf16 v[48:63], v[10:13], v[88:91], v[48:63]
	ds_read_b128 v[10:13], v137 offset:96
	s_waitcnt lgkmcnt(0)
	v_mfma_f32_32x32x16_bf16 v[48:63], v[10:13], v[92:95], v[48:63]
	ds_read_b128 v[10:13], v137 offset:128
	s_waitcnt lgkmcnt(0)
	v_mfma_f32_32x32x16_bf16 v[48:63], v[10:13], v[96:99], v[48:63]
	ds_read_b128 v[10:13], v137 offset:160
	s_waitcnt lgkmcnt(0)
	v_mfma_f32_32x32x16_bf16 v[48:63], v[10:13], v[100:103], v[48:63]
	ds_read_b128 v[10:13], v137 offset:6656
	s_waitcnt lgkmcnt(0)
	v_mfma_f32_32x32x16_bf16 v[64:79], v[10:13], v[80:83], 0
	ds_read_b128 v[10:13], v137 offset:6688
	s_waitcnt lgkmcnt(0)
	v_mfma_f32_32x32x16_bf16 v[64:79], v[10:13], v[84:87], v[64:79]
	ds_read_b128 v[10:13], v137 offset:6720
	s_waitcnt lgkmcnt(0)
	v_mfma_f32_32x32x16_bf16 v[64:79], v[10:13], v[88:91], v[64:79]
	ds_read_b128 v[10:13], v137 offset:6752
	s_waitcnt lgkmcnt(0)
	v_mfma_f32_32x32x16_bf16 v[64:79], v[10:13], v[92:95], v[64:79]
	ds_read_b128 v[10:13], v137 offset:6784
	s_waitcnt lgkmcnt(0)
	v_mfma_f32_32x32x16_bf16 v[64:79], v[10:13], v[96:99], v[64:79]
	ds_read_b128 v[10:13], v137 offset:6816
	s_waitcnt lgkmcnt(0)
	v_mfma_f32_32x32x16_bf16 v[64:79], v[10:13], v[100:103], v[64:79]
	s_nop 11
	v_max_f32_e32 v0, v49, v65
	v_max_f32_e32 v10, v50, v66
	v_max3_f32 v0, v48, v64, v0
	v_max_f32_e32 v11, v51, v67
	v_max3_f32 v0, v0, v10, v11
	v_max_f32_e32 v10, v52, v68
	v_max_f32_e32 v11, v53, v69
	v_max3_f32 v0, v0, v10, v11
	v_max_f32_e32 v10, v54, v70
	v_max_f32_e32 v11, v55, v71
	v_max3_f32 v0, v0, v10, v11
	v_max_f32_e32 v10, v56, v72
	v_max_f32_e32 v11, v57, v73
	v_max3_f32 v0, v0, v10, v11
	v_max_f32_e32 v10, v58, v74
	v_max_f32_e32 v11, v59, v75
	v_max3_f32 v0, v0, v10, v11
	v_max_f32_e32 v10, v60, v76
	v_max_f32_e32 v11, v61, v77
	v_max3_f32 v0, v0, v10, v11
	v_max_f32_e32 v10, v62, v78
	v_max_f32_e32 v11, v63, v79
	v_max3_f32 v0, v0, v10, v11
	v_sub_f32_e32 v10, v0, v142
	v_cmp_ge_f32_e32 vcc, s7, v10
	s_cmp_eq_u64 vcc, exec
	s_cbranch_scc1 .LBB0_233
	v_cmp_lt_i32_e32 vcc, v232, v226
	s_nop 1
	v_cndmask_b32_e32 v10, v224, v232, vcc
	v_lshlrev_b32_e32 v10, 2, v10
	ds_bpermute_b32 v10, v10, v0
	s_waitcnt lgkmcnt(0)
	v_max3_f32 v10, v142, v0, v10
	v_sub_f32_e32 v0, v142, v10
	v_exp_f32_e32 v0, v0
	v_mov_b32_e32 v142, v10
	v_mul_f32_e32 v143, v143, v0
	v_pk_mul_f32 v[46:47], v[46:47], v[0:1] op_sel_hi:[1,0]
	v_pk_mul_f32 v[44:45], v[44:45], v[0:1] op_sel_hi:[1,0]
	v_pk_mul_f32 v[42:43], v[42:43], v[0:1] op_sel_hi:[1,0]
	v_pk_mul_f32 v[40:41], v[40:41], v[0:1] op_sel_hi:[1,0]
	v_pk_mul_f32 v[38:39], v[38:39], v[0:1] op_sel_hi:[1,0]
	v_pk_mul_f32 v[36:37], v[36:37], v[0:1] op_sel_hi:[1,0]
	v_pk_mul_f32 v[34:35], v[34:35], v[0:1] op_sel_hi:[1,0]
	v_pk_mul_f32 v[32:33], v[32:33], v[0:1] op_sel_hi:[1,0]
	v_pk_mul_f32 v[30:31], v[30:31], v[0:1] op_sel_hi:[1,0]
	v_pk_mul_f32 v[28:29], v[28:29], v[0:1] op_sel_hi:[1,0]
	v_pk_mul_f32 v[26:27], v[26:27], v[0:1] op_sel_hi:[1,0]
	v_pk_mul_f32 v[24:25], v[24:25], v[0:1] op_sel_hi:[1,0]
	v_pk_mul_f32 v[22:23], v[22:23], v[0:1] op_sel_hi:[1,0]
	v_pk_mul_f32 v[20:21], v[20:21], v[0:1] op_sel_hi:[1,0]
	v_pk_mul_f32 v[18:19], v[18:19], v[0:1] op_sel_hi:[1,0]
	v_pk_mul_f32 v[16:17], v[16:17], v[0:1] op_sel_hi:[1,0]

.LBB0_237:
	s_or_b64 exec, exec, s[8:9]
	v_add_f32_e32 v0, v10, v0
	v_add_f32_e32 v0, 0, v0
	v_add_f32_e32 v10, v12, v11
	v_add_f32_e32 v0, v10, v0
	v_add_f32_e32 v10, v14, v13
	v_add_f32_e32 v0, v10, v0
	v_add_f32_e32 v10, v48, v15
	v_add_f32_e32 v0, v10, v0
	v_add_f32_e32 v10, v50, v49
	v_add_f32_e32 v0, v10, v0
	v_add_f32_e32 v10, v52, v51
	v_add_f32_e32 v0, v10, v0
	v_add_f32_e32 v10, v54, v53
	v_add_f32_e32 v0, v10, v0
	v_add_f32_e32 v10, v64, v55
	v_add_f32_e32 v0, v10, v0
	v_add_f32_e32 v10, v65, v56
	v_add_f32_e32 v0, v10, v0
	v_add_f32_e32 v10, v66, v57
	v_add_f32_e32 v0, v10, v0
	v_add_f32_e32 v10, v67, v58
	v_add_f32_e32 v0, v10, v0
	v_add_f32_e32 v10, v68, v59
	v_add_f32_e32 v0, v10, v0
	v_add_f32_e32 v10, v69, v60
	v_add_f32_e32 v0, v10, v0
	v_add_f32_e32 v10, v70, v61
	v_add_f32_e32 v0, v10, v0
	v_add_f32_e32 v10, v71, v62
	v_add_f32_e32 v0, v10, v0
	v_add_f32_e32 v10, v72, v63
	v_add_f32_e32 v0, v10, v0
	global_load_dwordx4 v[116:119], v[120:121], off offset:384
	ds_read_b128 v[10:13], v137 offset:22528
	ds_read_b128 v[64:67], v137 offset:22560
	s_waitcnt lgkmcnt(1)
	v_mfma_f32_32x32x16_bf16 v[48:63], v[10:13], v[80:83], 0
	ds_read_b128 v[10:13], v137 offset:22592
	v_add_f32_e32 v0, v143, v0
	s_waitcnt lgkmcnt(1)
	v_mfma_f32_32x32x16_bf16 v[48:63], v[64:67], v[84:87], v[48:63]
	s_waitcnt lgkmcnt(0)
	v_mfma_f32_32x32x16_bf16 v[48:63], v[10:13], v[88:91], v[48:63]
	ds_read_b128 v[10:13], v137 offset:22624
	s_waitcnt lgkmcnt(0)
	v_mfma_f32_32x32x16_bf16 v[48:63], v[10:13], v[92:95], v[48:63]
	ds_read_b128 v[10:13], v137 offset:22656
	s_waitcnt lgkmcnt(0)
	v_mfma_f32_32x32x16_bf16 v[48:63], v[10:13], v[96:99], v[48:63]
	ds_read_b128 v[10:13], v137 offset:22688
	s_waitcnt lgkmcnt(0)
	v_mfma_f32_32x32x16_bf16 v[48:63], v[10:13], v[100:103], v[48:63]
	ds_read_b128 v[10:13], v137 offset:29184
	s_waitcnt lgkmcnt(0)
	v_mfma_f32_32x32x16_bf16 v[64:79], v[10:13], v[80:83], 0
	ds_read_b128 v[10:13], v137 offset:29216
	s_waitcnt lgkmcnt(0)
	v_mfma_f32_32x32x16_bf16 v[64:79], v[10:13], v[84:87], v[64:79]
	ds_read_b128 v[10:13], v137 offset:29248
	s_waitcnt lgkmcnt(0)
	v_mfma_f32_32x32x16_bf16 v[64:79], v[10:13], v[88:91], v[64:79]
	ds_read_b128 v[10:13], v137 offset:29280
	s_waitcnt lgkmcnt(0)
	v_mfma_f32_32x32x16_bf16 v[64:79], v[10:13], v[92:95], v[64:79]
	ds_read_b128 v[10:13], v137 offset:29312
	s_waitcnt lgkmcnt(0)
	v_mfma_f32_32x32x16_bf16 v[64:79], v[10:13], v[96:99], v[64:79]
	ds_read_b128 v[10:13], v137 offset:29344
	s_waitcnt lgkmcnt(0)
	v_mfma_f32_32x32x16_bf16 v[64:79], v[10:13], v[100:103], v[64:79]
	s_nop 11
	v_max_f32_e32 v10, v49, v65
	v_max_f32_e32 v11, v50, v66
	v_max3_f32 v10, v48, v64, v10
	v_max_f32_e32 v12, v51, v67
	v_max3_f32 v10, v10, v11, v12
	v_max_f32_e32 v11, v52, v68
	v_max_f32_e32 v12, v53, v69
	v_max3_f32 v10, v10, v11, v12
	v_max_f32_e32 v11, v54, v70
	v_max_f32_e32 v12, v55, v71
	v_max3_f32 v10, v10, v11, v12
	v_max_f32_e32 v11, v56, v72
	v_max_f32_e32 v12, v57, v73
	v_max3_f32 v10, v10, v11, v12
	v_max_f32_e32 v11, v58, v74
	v_max_f32_e32 v12, v59, v75
	v_max3_f32 v10, v10, v11, v12
	v_max_f32_e32 v11, v60, v76
	v_max_f32_e32 v12, v61, v77
	v_max3_f32 v10, v10, v11, v12
	v_max_f32_e32 v11, v62, v78
	v_max_f32_e32 v12, v63, v79
	v_max3_f32 v10, v10, v11, v12
	v_sub_f32_e32 v11, v10, v142
	v_cmp_ge_f32_e32 vcc, s7, v11
	s_cmp_eq_u64 vcc, exec
	s_cbranch_scc1 .LBB0_239
	v_cmp_lt_i32_e32 vcc, v232, v226
	s_nop 1
	v_cndmask_b32_e32 v11, v224, v232, vcc
	v_lshlrev_b32_e32 v11, 2, v11
	ds_bpermute_b32 v11, v11, v10
	s_waitcnt lgkmcnt(0)
	v_max3_f32 v11, v142, v10, v11
	v_sub_f32_e32 v10, v142, v11
	v_exp_f32_e32 v10, v10
	v_mov_b32_e32 v142, v11
	v_mul_f32_e32 v0, v0, v10
	v_pk_mul_f32 v[46:47], v[46:47], v[10:11] op_sel_hi:[1,0]
	v_pk_mul_f32 v[44:45], v[44:45], v[10:11] op_sel_hi:[1,0]
	v_pk_mul_f32 v[42:43], v[42:43], v[10:11] op_sel_hi:[1,0]
	v_pk_mul_f32 v[40:41], v[40:41], v[10:11] op_sel_hi:[1,0]
	v_pk_mul_f32 v[38:39], v[38:39], v[10:11] op_sel_hi:[1,0]
	v_pk_mul_f32 v[36:37], v[36:37], v[10:11] op_sel_hi:[1,0]
	v_pk_mul_f32 v[34:35], v[34:35], v[10:11] op_sel_hi:[1,0]
	v_pk_mul_f32 v[32:33], v[32:33], v[10:11] op_sel_hi:[1,0]
	v_pk_mul_f32 v[30:31], v[30:31], v[10:11] op_sel_hi:[1,0]
	v_pk_mul_f32 v[28:29], v[28:29], v[10:11] op_sel_hi:[1,0]
	v_pk_mul_f32 v[26:27], v[26:27], v[10:11] op_sel_hi:[1,0]
	v_pk_mul_f32 v[24:25], v[24:25], v[10:11] op_sel_hi:[1,0]
	v_pk_mul_f32 v[22:23], v[22:23], v[10:11] op_sel_hi:[1,0]
	v_pk_mul_f32 v[20:21], v[20:21], v[10:11] op_sel_hi:[1,0]
	v_pk_mul_f32 v[18:19], v[18:19], v[10:11] op_sel_hi:[1,0]
	v_pk_mul_f32 v[16:17], v[16:17], v[10:11] op_sel_hi:[1,0]

.LBB0_262:
	v_add_u32_e32 v2, s2, v108
	v_ashrrev_i32_e32 v3, 31, v2
	v_lshlrev_b64 v[2:3], 8, v[2:3]
	v_lshl_add_u64 v[2:3], v[112:113], 0, v[2:3]
	v_lshl_add_u64 v[6:7], s[2:3], 1, v[110:111]
	v_add_u32_e32 v120, 0, v116
	global_load_dwordx4 v[2:5], v[2:3], off
	s_nop 0
	global_load_dwordx4 v[6:9], v[6:7], off
	ds_read_b128 v[10:13], v120
	ds_read_b128 v[64:67], v120 offset:32
	s_waitcnt lgkmcnt(1)
	v_mfma_f32_32x32x16_bf16 v[48:63], v[10:13], v[80:83], 0
	ds_read_b128 v[10:13], v120 offset:64
	s_waitcnt lgkmcnt(1)
	v_mfma_f32_32x32x16_bf16 v[48:63], v[64:67], v[84:87], v[48:63]
	s_waitcnt lgkmcnt(0)
	v_mfma_f32_32x32x16_bf16 v[48:63], v[10:13], v[88:91], v[48:63]
	ds_read_b128 v[10:13], v120 offset:96
	s_waitcnt lgkmcnt(0)
	v_mfma_f32_32x32x16_bf16 v[48:63], v[10:13], v[92:95], v[48:63]
	ds_read_b128 v[10:13], v120 offset:4608
	s_waitcnt lgkmcnt(0)
	v_mfma_f32_32x32x16_bf16 v[64:79], v[10:13], v[80:83], 0
	ds_read_b128 v[10:13], v120 offset:4640
	s_waitcnt lgkmcnt(0)
	v_mfma_f32_32x32x16_bf16 v[64:79], v[10:13], v[84:87], v[64:79]
	ds_read_b128 v[10:13], v120 offset:4672
	s_waitcnt lgkmcnt(0)
	v_mfma_f32_32x32x16_bf16 v[64:79], v[10:13], v[88:91], v[64:79]
	ds_read_b128 v[10:13], v120 offset:4704
	s_waitcnt lgkmcnt(0)
	v_mfma_f32_32x32x16_bf16 v[64:79], v[10:13], v[92:95], v[64:79]
	s_nop 11
	v_max_f32_e32 v0, v49, v65
	v_max_f32_e32 v10, v50, v66
	v_max3_f32 v0, v48, v64, v0
	v_max_f32_e32 v11, v51, v67
	v_max3_f32 v0, v0, v10, v11
	v_max_f32_e32 v10, v52, v68
	v_max_f32_e32 v11, v53, v69
	v_max3_f32 v0, v0, v10, v11
	v_max_f32_e32 v10, v54, v70
	v_max_f32_e32 v11, v55, v71
	v_max3_f32 v0, v0, v10, v11
	v_max_f32_e32 v10, v56, v72
	v_max_f32_e32 v11, v57, v73
	v_max3_f32 v0, v0, v10, v11
	v_max_f32_e32 v10, v58, v74
	v_max_f32_e32 v11, v59, v75
	v_max3_f32 v0, v0, v10, v11
	v_max_f32_e32 v10, v60, v76
	v_max_f32_e32 v11, v61, v77
	v_max3_f32 v0, v0, v10, v11
	v_max_f32_e32 v10, v62, v78
	v_max_f32_e32 v11, v63, v79
	v_max3_f32 v0, v0, v10, v11
	v_sub_f32_e32 v10, v0, v119
	v_cmp_ge_f32_e32 vcc, s7, v10
	s_cmp_eq_u64 vcc, exec
	s_cbranch_scc1 .LBB0_264
	v_cmp_lt_i32_e32 vcc, v232, v226
	s_nop 1
	v_cndmask_b32_e32 v10, v224, v232, vcc
	v_lshlrev_b32_e32 v10, 2, v10
	ds_bpermute_b32 v10, v10, v0
	s_waitcnt lgkmcnt(0)
	v_max3_f32 v10, v119, v0, v10
	v_sub_f32_e32 v0, v119, v10
	v_exp_f32_e32 v0, v0
	v_mov_b32_e32 v119, v10
	v_mul_f32_e32 v121, v121, v0
	v_pk_mul_f32 v[46:47], v[46:47], v[0:1] op_sel_hi:[1,0]
	v_pk_mul_f32 v[44:45], v[44:45], v[0:1] op_sel_hi:[1,0]
	v_pk_mul_f32 v[42:43], v[42:43], v[0:1] op_sel_hi:[1,0]
	v_pk_mul_f32 v[40:41], v[40:41], v[0:1] op_sel_hi:[1,0]
	v_pk_mul_f32 v[38:39], v[38:39], v[0:1] op_sel_hi:[1,0]
	v_pk_mul_f32 v[36:37], v[36:37], v[0:1] op_sel_hi:[1,0]
	v_pk_mul_f32 v[34:35], v[34:35], v[0:1] op_sel_hi:[1,0]
	v_pk_mul_f32 v[32:33], v[32:33], v[0:1] op_sel_hi:[1,0]
	v_pk_mul_f32 v[30:31], v[30:31], v[0:1] op_sel_hi:[1,0]
	v_pk_mul_f32 v[28:29], v[28:29], v[0:1] op_sel_hi:[1,0]
	v_pk_mul_f32 v[26:27], v[26:27], v[0:1] op_sel_hi:[1,0]
	v_pk_mul_f32 v[24:25], v[24:25], v[0:1] op_sel_hi:[1,0]
	v_pk_mul_f32 v[22:23], v[22:23], v[0:1] op_sel_hi:[1,0]
	v_pk_mul_f32 v[20:21], v[20:21], v[0:1] op_sel_hi:[1,0]
	v_pk_mul_f32 v[18:19], v[18:19], v[0:1] op_sel_hi:[1,0]
	v_pk_mul_f32 v[16:17], v[16:17], v[0:1] op_sel_hi:[1,0]
.LBB0_264:
	v_sub_f32_e32 v0, v48, v119
	v_exp_f32_e32 v122, v0
	v_sub_f32_e32 v0, v64, v119
	v_exp_f32_e32 v123, v0
	v_sub_f32_e32 v0, v49, v119
	v_sub_f32_e32 v10, v65, v119
	v_exp_f32_e32 v0, v0
	v_exp_f32_e32 v10, v10
	v_add_f32_e32 v11, v123, v122
	v_pk_add_f32 v[12:13], v[10:11], v[0:1]
	v_sub_f32_e32 v11, v50, v119
	v_exp_f32_e32 v124, v11
	v_sub_f32_e32 v11, v66, v119
	v_pk_add_f32 v[64:65], v[12:13], v[12:13] op_sel_hi:[0,1]
	v_exp_f32_e32 v125, v11
	v_sub_f32_e32 v11, v51, v119
	v_exp_f32_e32 v64, v11
	v_sub_f32_e32 v11, v67, v119
	v_exp_f32_e32 v12, v11
	v_add_f32_e32 v13, v125, v124
	v_sub_f32_e32 v11, v52, v119
	v_pk_add_f32 v[14:15], v[12:13], v[64:65]
	v_exp_f32_e32 v13, v11
	v_sub_f32_e32 v11, v68, v119
	v_pk_add_f32 v[66:67], v[14:15], v[14:15] op_sel_hi:[0,1]
	v_exp_f32_e32 v126, v11
	v_sub_f32_e32 v11, v53, v119
	v_exp_f32_e32 v66, v11
	v_sub_f32_e32 v11, v69, v119
	v_exp_f32_e32 v14, v11
	v_add_f32_e32 v15, v126, v13
	v_sub_f32_e32 v11, v54, v119
	v_pk_add_f32 v[48:49], v[14:15], v[66:67]
	v_exp_f32_e32 v15, v11
	v_sub_f32_e32 v11, v70, v119
	v_pk_add_f32 v[68:69], v[48:49], v[48:49] op_sel_hi:[0,1]
	v_exp_f32_e32 v127, v11
	v_sub_f32_e32 v11, v55, v119
	v_exp_f32_e32 v68, v11
	v_sub_f32_e32 v11, v71, v119
	v_exp_f32_e32 v48, v11
	v_add_f32_e32 v49, v127, v15
	v_sub_f32_e32 v11, v56, v119
	v_pk_add_f32 v[50:51], v[48:49], v[68:69]
	v_exp_f32_e32 v49, v11
	v_sub_f32_e32 v11, v72, v119
	v_pk_add_f32 v[70:71], v[50:51], v[50:51] op_sel_hi:[0,1]
	v_exp_f32_e32 v128, v11
	v_sub_f32_e32 v11, v57, v119
	v_exp_f32_e32 v70, v11
	v_sub_f32_e32 v11, v73, v119
	v_exp_f32_e32 v50, v11
	v_add_f32_e32 v51, v128, v49
	v_sub_f32_e32 v11, v58, v119
	v_pk_add_f32 v[52:53], v[50:51], v[70:71]
	v_exp_f32_e32 v51, v11
	v_sub_f32_e32 v11, v74, v119
	v_pk_add_f32 v[72:73], v[52:53], v[52:53] op_sel_hi:[0,1]
	v_exp_f32_e32 v71, v11
	v_sub_f32_e32 v11, v59, v119
	v_exp_f32_e32 v72, v11
	v_sub_f32_e32 v11, v75, v119
	v_exp_f32_e32 v52, v11
	v_add_f32_e32 v53, v71, v51
	v_sub_f32_e32 v11, v60, v119
	v_cvt_pk_bf16_f32 v60, v13, v66
	v_pk_add_f32 v[54:55], v[52:53], v[72:73]
	v_exp_f32_e32 v53, v11
	v_sub_f32_e32 v11, v76, v119
	v_pk_add_f32 v[74:75], v[54:55], v[54:55] op_sel_hi:[0,1]
	v_exp_f32_e32 v73, v11
	v_sub_f32_e32 v11, v61, v119
	v_exp_f32_e32 v74, v11
	v_sub_f32_e32 v11, v77, v119
	v_exp_f32_e32 v54, v11
	v_add_f32_e32 v55, v73, v53
	v_sub_f32_e32 v11, v62, v119
	v_cvt_pk_bf16_f32 v61, v15, v68
	v_pk_add_f32 v[56:57], v[54:55], v[74:75]
	v_exp_f32_e32 v55, v11
	v_sub_f32_e32 v11, v78, v119
	v_pk_add_f32 v[76:77], v[56:57], v[56:57] op_sel_hi:[0,1]
	v_exp_f32_e32 v75, v11
	v_sub_f32_e32 v11, v63, v119
	v_exp_f32_e32 v76, v11
	v_sub_f32_e32 v11, v79, v119
	v_exp_f32_e32 v56, v11
	v_add_f32_e32 v57, v75, v55
	v_pk_add_f32 v[58:59], v[56:57], v[76:77]
	s_nop 0
	v_add_f32_e32 v11, v58, v59
	v_cvt_pk_bf16_f32 v58, v122, v0
	v_add_u32_e32 v0, 0x2000, v117
	v_cvt_pk_bf16_f32 v59, v124, v64
	ds_read2_b64 v[62:65], v0 offset0:128 offset1:130
	v_add_u32_e32 v0, 0x3000, v118
	s_waitcnt lgkmcnt(0)
	v_mfma_f32_32x32x16_bf16 v[32:47], v[62:65], v[58:61], v[32:47]
	ds_read2_b64 v[62:65], v0 offset0:192 offset1:194
	v_add_f32_e32 v11, v121, v11
	s_waitcnt lgkmcnt(0)
	v_mfma_f32_32x32x16_bf16 v[16:31], v[62:65], v[58:61], v[16:31]
	v_cvt_pk_bf16_f32 v58, v49, v70
	v_add_u32_e32 v49, 0x2000, v118
	ds_read2_b64 v[62:65], v49 offset0:132 offset1:134
	ds_read2_b64 v[66:69], v49 offset0:136 offset1:138
	v_cvt_pk_bf16_f32 v59, v51, v72
	v_cvt_pk_bf16_f32 v60, v53, v74
	v_cvt_pk_bf16_f32 v61, v55, v76
	s_waitcnt lgkmcnt(1)
	s_nop 0
	v_mfma_f32_32x32x16_bf16 v[32:47], v[62:65], v[58:61], v[32:47]
	ds_read2_b64 v[62:65], v0 offset0:196 offset1:198
	s_waitcnt lgkmcnt(0)
	v_mfma_f32_32x32x16_bf16 v[16:31], v[62:65], v[58:61], v[16:31]
	v_cvt_pk_bf16_f32 v59, v125, v12
	v_cvt_pk_bf16_f32 v60, v126, v14
	ds_read2_b64 v[12:15], v0 offset0:200 offset1:202
	v_cvt_pk_bf16_f32 v58, v123, v10
	v_cvt_pk_bf16_f32 v61, v127, v48
	s_waitcnt lgkmcnt(0)
	s_nop 0
	v_mfma_f32_32x32x16_bf16 v[16:31], v[12:15], v[58:61], v[16:31]
	v_cvt_pk_bf16_f32 v12, v128, v50
	ds_read2_b64 v[48:51], v49 offset0:140 offset1:142
	v_cvt_pk_bf16_f32 v13, v71, v52
	v_cvt_pk_bf16_f32 v14, v73, v54
	v_cvt_pk_bf16_f32 v15, v75, v56
	v_mfma_f32_32x32x16_bf16 v[32:47], v[66:69], v[58:61], v[32:47]
	s_waitcnt lgkmcnt(0)
	v_mfma_f32_32x32x16_bf16 v[32:47], v[48:51], v[12:15], v[32:47]
	ds_read2_b64 v[48:51], v0 offset0:204 offset1:206
	s_waitcnt vmcnt(3)
	ds_write_b128 v107, v[96:99] offset:18432
	s_waitcnt vmcnt(2)
	ds_write_b128 v109, v[100:103] offset:27648
	s_waitcnt lgkmcnt(0)
	s_barrier
	global_load_dwordx4 v[96:99], v[114:115], off
	global_load_dwordx4 v[100:103], v[110:111], off offset:384
	s_waitcnt lgkmcnt(2)
	v_mfma_f32_32x32x16_bf16 v[16:31], v[48:51], v[12:15], v[16:31]
	ds_read_b128 v[12:15], v120 offset:18432
	ds_read_b128 v[48:51], v120 offset:18464
	s_waitcnt lgkmcnt(1)
	v_mfma_f32_32x32x16_bf16 v[64:79], v[12:15], v[80:83], 0
	ds_read_b128 v[12:15], v120 offset:18496
	s_waitcnt lgkmcnt(1)
	v_mfma_f32_32x32x16_bf16 v[64:79], v[48:51], v[84:87], v[64:79]
	s_waitcnt lgkmcnt(0)
	v_mfma_f32_32x32x16_bf16 v[64:79], v[12:15], v[88:91], v[64:79]
	ds_read_b128 v[12:15], v120 offset:18528
	s_waitcnt lgkmcnt(0)
	v_mfma_f32_32x32x16_bf16 v[64:79], v[12:15], v[92:95], v[64:79]
	ds_read_b128 v[12:15], v120 offset:23040
	s_waitcnt lgkmcnt(0)
	v_mfma_f32_32x32x16_bf16 v[48:63], v[12:15], v[80:83], 0
	ds_read_b128 v[12:15], v120 offset:23072
	s_nop 7
	v_max_f32_e32 v10, v65, v65
	s_waitcnt lgkmcnt(0)
	v_mfma_f32_32x32x16_bf16 v[48:63], v[12:15], v[84:87], v[48:63]
	ds_read_b128 v[12:15], v120 offset:23104
	s_waitcnt lgkmcnt(0)
	v_mfma_f32_32x32x16_bf16 v[48:63], v[12:15], v[88:91], v[48:63]
	ds_read_b128 v[12:15], v120 offset:23136
	s_waitcnt lgkmcnt(0)
	v_mfma_f32_32x32x16_bf16 v[48:63], v[12:15], v[92:95], v[48:63]
	s_nop 11
	v_max_f32_e32 v0, v10, v49
	v_max_f32_e32 v10, v66, v50
	v_max3_f32 v0, v64, v48, v0
	v_max_f32_e32 v12, v67, v51
	v_max3_f32 v0, v0, v10, v12
	v_max_f32_e32 v10, v68, v52
	v_max_f32_e32 v12, v69, v53
	v_max3_f32 v0, v0, v10, v12
	v_max_f32_e32 v10, v70, v54
	v_max_f32_e32 v12, v71, v55
	v_max3_f32 v0, v0, v10, v12
	v_max_f32_e32 v10, v72, v56
	v_max_f32_e32 v12, v73, v57
	v_max3_f32 v0, v0, v10, v12
	v_max_f32_e32 v10, v74, v58
	v_max_f32_e32 v12, v75, v59
	v_max3_f32 v0, v0, v10, v12
	v_max_f32_e32 v10, v76, v60
	v_max_f32_e32 v12, v77, v61
	v_max3_f32 v0, v0, v10, v12
	v_max_f32_e32 v10, v78, v62
	v_max_f32_e32 v12, v79, v63
	v_max3_f32 v0, v0, v10, v12
	v_sub_f32_e32 v10, v0, v119
	v_cmp_ge_f32_e32 vcc, s7, v10
	s_cmp_eq_u64 vcc, exec
	s_cbranch_scc1 .LBB0_261
	v_cmp_lt_i32_e32 vcc, v232, v226
	s_nop 1
	v_cndmask_b32_e32 v10, v224, v232, vcc
	v_lshlrev_b32_e32 v10, 2, v10
	ds_bpermute_b32 v10, v10, v0
	s_waitcnt lgkmcnt(0)
	v_max3_f32 v10, v119, v0, v10
	v_sub_f32_e32 v0, v119, v10
	v_exp_f32_e32 v0, v0
	v_mov_b32_e32 v119, v10
	v_mul_f32_e32 v11, v11, v0
	v_pk_mul_f32 v[46:47], v[46:47], v[0:1] op_sel_hi:[1,0]
	v_pk_mul_f32 v[44:45], v[44:45], v[0:1] op_sel_hi:[1,0]
	v_pk_mul_f32 v[42:43], v[42:43], v[0:1] op_sel_hi:[1,0]
	v_pk_mul_f32 v[40:41], v[40:41], v[0:1] op_sel_hi:[1,0]
	v_pk_mul_f32 v[38:39], v[38:39], v[0:1] op_sel_hi:[1,0]
	v_pk_mul_f32 v[36:37], v[36:37], v[0:1] op_sel_hi:[1,0]
	v_pk_mul_f32 v[34:35], v[34:35], v[0:1] op_sel_hi:[1,0]
	v_pk_mul_f32 v[32:33], v[32:33], v[0:1] op_sel_hi:[1,0]
	v_pk_mul_f32 v[30:31], v[30:31], v[0:1] op_sel_hi:[1,0]
	v_pk_mul_f32 v[28:29], v[28:29], v[0:1] op_sel_hi:[1,0]
	v_pk_mul_f32 v[26:27], v[26:27], v[0:1] op_sel_hi:[1,0]
	v_pk_mul_f32 v[24:25], v[24:25], v[0:1] op_sel_hi:[1,0]
	v_pk_mul_f32 v[22:23], v[22:23], v[0:1] op_sel_hi:[1,0]
	v_pk_mul_f32 v[20:21], v[20:21], v[0:1] op_sel_hi:[1,0]
	v_pk_mul_f32 v[18:19], v[18:19], v[0:1] op_sel_hi:[1,0]
	v_pk_mul_f32 v[16:17], v[16:17], v[0:1] op_sel_hi:[1,0]
	s_branch .LBB0_261
